# K-loop MFMA blocks in snake order (every consecutive MFMA pair shares a source operand register): operand-read energy experiment, same bytes and layout
# baseline (speedup 1.0000x reference)
.LBB0_75:
	s_add_u32 s68, s90, 0xfffc0080
	s_addc_u32 s69, s91, -1
	s_add_i32 s70, 0, 0x10000
	s_cmp_eq_u32 s97, 12
	s_cselect_b32 s95, s2, s69
	s_cselect_b32 s94, s6, s68
	v_add_u32_e32 v140, s70, v151
	s_cselect_b32 s93, s51, s96
	s_cselect_b32 s92, s63, s89
	s_add_i32 s71, 0, 0x14000
	s_waitcnt vmcnt(0)
	ds_read_b128 v[154:157], v140
	ds_read_b128 v[158:161], v140 offset:1024
	ds_read_b128 v[162:165], v140 offset:2048
	ds_read_b128 v[166:169], v140 offset:3072
	v_add_u32_e32 v140, s71, v151
	ds_read_b128 v[170:173], v140
	ds_read_b128 v[174:177], v140 offset:1024
	ds_read_b128 v[178:181], v140 offset:2048
	ds_read_b128 v[182:185], v140 offset:3072
	v_lshl_add_u64 v[140:141], s[90:91], 0, v[136:137]
	s_add_i32 m0, s18, 0xc000
	ds_read_b128 v[186:189], v153
	ds_read_b128 v[190:193], v153 offset:1024
	ds_read_b128 v[194:197], v153 offset:2048
	ds_read_b128 v[198:201], v153 offset:3072
	ds_read_b128 v[202:205], v153 offset:4096
	ds_read_b128 v[210:213], v153 offset:5120
	ds_read_b128 v[214:217], v153 offset:6144
	ds_read_b128 v[218:221], v153 offset:7168
	global_load_lds_dwordx4 v[140:141], off
	v_lshl_add_u64 v[140:141], s[90:91], 0, v[138:139]
	s_add_i32 m0, s18, 0xe000
	s_nop 0
	global_load_lds_dwordx4 v[140:141], off
	s_waitcnt vmcnt(8)
	s_waitcnt lgkmcnt(0)
	s_barrier
	s_waitcnt lgkmcnt(0)
	v_mfma_f32_16x16x32_bf16 v[126:129], v[154:157], v[186:189], v[126:129]
	v_mfma_f32_16x16x32_bf16 v[122:125], v[162:165], v[186:189], v[122:125]
	v_mfma_f32_16x16x32_bf16 v[106:109], v[162:165], v[194:197], v[106:109]
	v_mfma_f32_16x16x32_bf16 v[110:113], v[154:157], v[194:197], v[110:113]
	v_mfma_f32_16x16x32_bf16 v[98:101], v[154:157], v[202:205], v[98:101]
	v_mfma_f32_16x16x32_bf16 v[90:93], v[162:165], v[202:205], v[90:93]
	v_mfma_f32_16x16x32_bf16 v[74:77], v[162:165], v[214:217], v[74:77]
	v_mfma_f32_16x16x32_bf16 v[82:85], v[154:157], v[214:217], v[82:85]
	v_mfma_f32_16x16x32_bf16 v[118:121], v[170:173], v[186:189], v[118:121]
	v_mfma_f32_16x16x32_bf16 v[114:117], v[178:181], v[186:189], v[114:117]
	v_mfma_f32_16x16x32_bf16 v[94:97], v[178:181], v[194:197], v[94:97]
	v_mfma_f32_16x16x32_bf16 v[102:105], v[170:173], v[194:197], v[102:105]
	v_mfma_f32_16x16x32_bf16 v[86:89], v[170:173], v[202:205], v[86:89]
	v_mfma_f32_16x16x32_bf16 v[78:81], v[178:181], v[202:205], v[78:81]
	v_mfma_f32_16x16x32_bf16 v[66:69], v[178:181], v[214:217], v[66:69]
	v_mfma_f32_16x16x32_bf16 v[70:73], v[170:173], v[214:217], v[70:73]
	v_mfma_f32_16x16x32_bf16 v[126:129], v[158:161], v[190:193], v[126:129]
	v_mfma_f32_16x16x32_bf16 v[122:125], v[166:169], v[190:193], v[122:125]
	v_mfma_f32_16x16x32_bf16 v[106:109], v[166:169], v[198:201], v[106:109]
	v_mfma_f32_16x16x32_bf16 v[110:113], v[158:161], v[198:201], v[110:113]
	v_mfma_f32_16x16x32_bf16 v[98:101], v[158:161], v[210:213], v[98:101]
	v_mfma_f32_16x16x32_bf16 v[90:93], v[166:169], v[210:213], v[90:93]
	v_mfma_f32_16x16x32_bf16 v[74:77], v[166:169], v[218:221], v[74:77]
	v_mfma_f32_16x16x32_bf16 v[82:85], v[158:161], v[218:221], v[82:85]
	v_mfma_f32_16x16x32_bf16 v[118:121], v[174:177], v[190:193], v[118:121]
	v_mfma_f32_16x16x32_bf16 v[114:117], v[182:185], v[190:193], v[114:117]
	v_mfma_f32_16x16x32_bf16 v[94:97], v[182:185], v[198:201], v[94:97]
	v_mfma_f32_16x16x32_bf16 v[102:105], v[174:177], v[198:201], v[102:105]
	v_mfma_f32_16x16x32_bf16 v[86:89], v[174:177], v[210:213], v[86:89]
	v_mfma_f32_16x16x32_bf16 v[78:81], v[182:185], v[210:213], v[78:81]
	v_mfma_f32_16x16x32_bf16 v[66:69], v[182:185], v[218:221], v[66:69]
	v_mfma_f32_16x16x32_bf16 v[70:73], v[174:177], v[218:221], v[70:73]
	s_barrier
	s_add_i32 s68, s70, s16
	v_lshl_add_u64 v[140:141], s[92:93], 0, v[0:1]
	s_mov_b32 m0, s68
	ds_read_b128 v[186:189], v153 offset:16384
	ds_read_b128 v[190:193], v153 offset:17408
	ds_read_b128 v[194:197], v153 offset:18432
	ds_read_b128 v[198:201], v153 offset:19456
	ds_read_b128 v[202:205], v153 offset:20480
	ds_read_b128 v[210:213], v153 offset:21504
	ds_read_b128 v[214:217], v153 offset:22528
	ds_read_b128 v[218:221], v153 offset:23552
	global_load_lds_dwordx4 v[140:141], off
	s_add_i32 m0, s68, 0x2000
	s_add_u32 s68, s92, 0x40000
	v_lshl_add_u64 v[144:145], s[92:93], 0, v[130:131]
	s_addc_u32 s69, s93, 0
	s_add_i32 s70, s71, s16
	global_load_lds_dwordx4 v[144:145], off
	v_lshl_add_u64 v[148:149], s[68:69], 0, v[0:1]
	s_mov_b32 m0, s70
	v_lshl_add_u64 v[206:207], s[94:95], 0, v[132:133]
	global_load_lds_dwordx4 v[148:149], off
	v_lshl_add_u64 v[148:149], s[68:69], 0, v[130:131]
	s_add_i32 m0, s70, 0x2000
	s_nop 0
	global_load_lds_dwordx4 v[148:149], off
	v_lshl_add_u64 v[148:149], s[94:95], 0, v[134:135]
	s_mov_b32 m0, s18
	s_nop 0
	global_load_lds_dwordx4 v[148:149], off
	s_mov_b32 m0, s19
	s_nop 0
	global_load_lds_dwordx4 v[206:207], off
	s_waitcnt vmcnt(8)
	s_waitcnt lgkmcnt(0)
	s_barrier
	s_waitcnt lgkmcnt(0)
	v_mfma_f32_16x16x32_bf16 v[62:65], v[154:157], v[186:189], v[62:65]
	v_mfma_f32_16x16x32_bf16 v[58:61], v[162:165], v[186:189], v[58:61]
	v_mfma_f32_16x16x32_bf16 v[42:45], v[162:165], v[194:197], v[42:45]
	v_mfma_f32_16x16x32_bf16 v[50:53], v[154:157], v[194:197], v[50:53]
	v_mfma_f32_16x16x32_bf16 v[34:37], v[154:157], v[202:205], v[34:37]
	v_mfma_f32_16x16x32_bf16 v[26:29], v[162:165], v[202:205], v[26:29]
	v_mfma_f32_16x16x32_bf16 v[10:13], v[162:165], v[214:217], v[10:13]
	v_mfma_f32_16x16x32_bf16 v[18:21], v[154:157], v[214:217], v[18:21]
	v_mfma_f32_16x16x32_bf16 v[54:57], v[170:173], v[186:189], v[54:57]
	v_mfma_f32_16x16x32_bf16 v[46:49], v[178:181], v[186:189], v[46:49]
	v_mfma_f32_16x16x32_bf16 v[30:33], v[178:181], v[194:197], v[30:33]
	v_mfma_f32_16x16x32_bf16 v[38:41], v[170:173], v[194:197], v[38:41]
	v_mfma_f32_16x16x32_bf16 v[22:25], v[170:173], v[202:205], v[22:25]
	v_mfma_f32_16x16x32_bf16 v[14:17], v[178:181], v[202:205], v[14:17]
	v_mfma_f32_16x16x32_bf16 v[2:5], v[178:181], v[214:217], v[2:5]
	v_mfma_f32_16x16x32_bf16 v[6:9], v[170:173], v[214:217], v[6:9]
	v_mfma_f32_16x16x32_bf16 v[62:65], v[158:161], v[190:193], v[62:65]
	v_mfma_f32_16x16x32_bf16 v[58:61], v[166:169], v[190:193], v[58:61]
	v_mfma_f32_16x16x32_bf16 v[42:45], v[166:169], v[198:201], v[42:45]
	v_mfma_f32_16x16x32_bf16 v[50:53], v[158:161], v[198:201], v[50:53]
	v_mfma_f32_16x16x32_bf16 v[34:37], v[158:161], v[210:213], v[34:37]
	v_mfma_f32_16x16x32_bf16 v[26:29], v[166:169], v[210:213], v[26:29]
	v_mfma_f32_16x16x32_bf16 v[10:13], v[166:169], v[218:221], v[10:13]
	v_mfma_f32_16x16x32_bf16 v[18:21], v[158:161], v[218:221], v[18:21]
	v_mfma_f32_16x16x32_bf16 v[54:57], v[174:177], v[190:193], v[54:57]
	v_mfma_f32_16x16x32_bf16 v[46:49], v[182:185], v[190:193], v[46:49]
	v_mfma_f32_16x16x32_bf16 v[30:33], v[182:185], v[198:201], v[30:33]
	v_mfma_f32_16x16x32_bf16 v[38:41], v[174:177], v[198:201], v[38:41]
	v_mfma_f32_16x16x32_bf16 v[22:25], v[174:177], v[210:213], v[22:25]
	v_mfma_f32_16x16x32_bf16 v[14:17], v[182:185], v[210:213], v[14:17]
	v_mfma_f32_16x16x32_bf16 v[2:5], v[182:185], v[218:221], v[2:5]
	v_mfma_f32_16x16x32_bf16 v[6:9], v[174:177], v[218:221], v[6:9]
	s_barrier
	s_add_i32 s70, 0, 0x18000
	v_add_u32_e32 v142, s70, v151
	s_add_i32 s71, 0, 0x1c000
	ds_read_b128 v[154:157], v142
	ds_read_b128 v[158:161], v142 offset:1024
	ds_read_b128 v[162:165], v142 offset:2048
	ds_read_b128 v[166:169], v142 offset:3072
	v_add_u32_e32 v142, s71, v151
	ds_read_b128 v[170:173], v142
	ds_read_b128 v[174:177], v142 offset:1024
	ds_read_b128 v[178:181], v142 offset:2048
	ds_read_b128 v[182:185], v142 offset:3072
	s_add_u32 s68, s94, 0x40000
	s_addc_u32 s69, s95, 0
	s_mov_b32 m0, s20
	v_lshl_add_u64 v[222:223], s[68:69], 0, v[134:135]
	ds_read_b128 v[186:189], v153 offset:32768
	ds_read_b128 v[190:193], v153 offset:33792
	ds_read_b128 v[194:197], v153 offset:34816
	ds_read_b128 v[198:201], v153 offset:35840
	ds_read_b128 v[202:205], v153 offset:36864
	ds_read_b128 v[210:213], v153 offset:37888
	ds_read_b128 v[214:217], v153 offset:38912
	ds_read_b128 v[218:221], v153 offset:39936
	global_load_lds_dwordx4 v[222:223], off
	v_lshl_add_u64 v[222:223], s[68:69], 0, v[132:133]
	s_mov_b32 m0, s21
	s_nop 0
	global_load_lds_dwordx4 v[222:223], off
	s_waitcnt vmcnt(8)
	s_waitcnt lgkmcnt(0)
	s_barrier
	s_waitcnt lgkmcnt(0)
	v_mfma_f32_16x16x32_bf16 v[126:129], v[154:157], v[186:189], v[126:129]
	v_mfma_f32_16x16x32_bf16 v[122:125], v[162:165], v[186:189], v[122:125]
	v_mfma_f32_16x16x32_bf16 v[106:109], v[162:165], v[194:197], v[106:109]
	v_mfma_f32_16x16x32_bf16 v[110:113], v[154:157], v[194:197], v[110:113]
	v_mfma_f32_16x16x32_bf16 v[98:101], v[154:157], v[202:205], v[98:101]
	v_mfma_f32_16x16x32_bf16 v[90:93], v[162:165], v[202:205], v[90:93]
	v_mfma_f32_16x16x32_bf16 v[74:77], v[162:165], v[214:217], v[74:77]
	v_mfma_f32_16x16x32_bf16 v[82:85], v[154:157], v[214:217], v[82:85]
	v_mfma_f32_16x16x32_bf16 v[118:121], v[170:173], v[186:189], v[118:121]
	v_mfma_f32_16x16x32_bf16 v[114:117], v[178:181], v[186:189], v[114:117]
	v_mfma_f32_16x16x32_bf16 v[94:97], v[178:181], v[194:197], v[94:97]
	v_mfma_f32_16x16x32_bf16 v[102:105], v[170:173], v[194:197], v[102:105]
	v_mfma_f32_16x16x32_bf16 v[86:89], v[170:173], v[202:205], v[86:89]
	v_mfma_f32_16x16x32_bf16 v[78:81], v[178:181], v[202:205], v[78:81]
	v_mfma_f32_16x16x32_bf16 v[66:69], v[178:181], v[214:217], v[66:69]
	v_mfma_f32_16x16x32_bf16 v[70:73], v[170:173], v[214:217], v[70:73]
	v_mfma_f32_16x16x32_bf16 v[126:129], v[158:161], v[190:193], v[126:129]
	v_mfma_f32_16x16x32_bf16 v[122:125], v[166:169], v[190:193], v[122:125]
	v_mfma_f32_16x16x32_bf16 v[106:109], v[166:169], v[198:201], v[106:109]
	v_mfma_f32_16x16x32_bf16 v[110:113], v[158:161], v[198:201], v[110:113]
	v_mfma_f32_16x16x32_bf16 v[98:101], v[158:161], v[210:213], v[98:101]
	v_mfma_f32_16x16x32_bf16 v[90:93], v[166:169], v[210:213], v[90:93]
	v_mfma_f32_16x16x32_bf16 v[74:77], v[166:169], v[218:221], v[74:77]
	v_mfma_f32_16x16x32_bf16 v[82:85], v[158:161], v[218:221], v[82:85]
	v_mfma_f32_16x16x32_bf16 v[118:121], v[174:177], v[190:193], v[118:121]
	v_mfma_f32_16x16x32_bf16 v[114:117], v[182:185], v[190:193], v[114:117]
	v_mfma_f32_16x16x32_bf16 v[94:97], v[182:185], v[198:201], v[94:97]
	v_mfma_f32_16x16x32_bf16 v[102:105], v[174:177], v[198:201], v[102:105]
	v_mfma_f32_16x16x32_bf16 v[86:89], v[174:177], v[210:213], v[86:89]
	v_mfma_f32_16x16x32_bf16 v[78:81], v[182:185], v[210:213], v[78:81]
	v_mfma_f32_16x16x32_bf16 v[66:69], v[182:185], v[218:221], v[66:69]
	v_mfma_f32_16x16x32_bf16 v[70:73], v[174:177], v[218:221], v[70:73]
	s_barrier
	s_add_i32 s68, s70, s16
	v_lshl_add_u64 v[140:141], v[140:141], 0, s[34:35]
	s_mov_b32 m0, s68
	ds_read_b128 v[186:189], v153 offset:49152
	ds_read_b128 v[190:193], v153 offset:50176
	ds_read_b128 v[194:197], v153 offset:51200
	ds_read_b128 v[198:201], v153 offset:52224
	ds_read_b128 v[202:205], v153 offset:53248
	ds_read_b128 v[210:213], v153 offset:54272
	ds_read_b128 v[214:217], v153 offset:55296
	ds_read_b128 v[218:221], v153 offset:56320
	global_load_lds_dwordx4 v[140:141], off
	s_add_i32 m0, s68, 0x2000
	s_add_u32 s68, s92, 0x40080
	v_lshl_add_u64 v[140:141], v[144:145], 0, s[34:35]
	s_addc_u32 s69, s93, 0
	s_add_i32 s70, s71, s16
	global_load_lds_dwordx4 v[140:141], off
	v_lshl_add_u64 v[140:141], s[68:69], 0, v[0:1]
	s_mov_b32 m0, s70
	s_nop 0
	global_load_lds_dwordx4 v[140:141], off
	v_lshl_add_u64 v[140:141], s[68:69], 0, v[130:131]
	s_add_i32 m0, s70, 0x2000
	s_nop 0
	global_load_lds_dwordx4 v[140:141], off
	v_lshl_add_u64 v[140:141], v[148:149], 0, s[34:35]
	s_mov_b32 m0, s23
	s_nop 0
	global_load_lds_dwordx4 v[140:141], off
	v_lshl_add_u64 v[140:141], v[206:207], 0, s[34:35]
	s_mov_b32 m0, s29
	s_nop 0
	global_load_lds_dwordx4 v[140:141], off
	s_waitcnt vmcnt(8)
	s_waitcnt lgkmcnt(0)
	s_barrier
	s_waitcnt lgkmcnt(0)
	v_mfma_f32_16x16x32_bf16 v[62:65], v[154:157], v[186:189], v[62:65]
	v_mfma_f32_16x16x32_bf16 v[58:61], v[162:165], v[186:189], v[58:61]
	v_mfma_f32_16x16x32_bf16 v[42:45], v[162:165], v[194:197], v[42:45]
	v_mfma_f32_16x16x32_bf16 v[50:53], v[154:157], v[194:197], v[50:53]
	v_mfma_f32_16x16x32_bf16 v[34:37], v[154:157], v[202:205], v[34:37]
	v_mfma_f32_16x16x32_bf16 v[26:29], v[162:165], v[202:205], v[26:29]
	v_mfma_f32_16x16x32_bf16 v[10:13], v[162:165], v[214:217], v[10:13]
	v_mfma_f32_16x16x32_bf16 v[18:21], v[154:157], v[214:217], v[18:21]
	v_mfma_f32_16x16x32_bf16 v[54:57], v[170:173], v[186:189], v[54:57]
	v_mfma_f32_16x16x32_bf16 v[46:49], v[178:181], v[186:189], v[46:49]
	v_mfma_f32_16x16x32_bf16 v[30:33], v[178:181], v[194:197], v[30:33]
	v_mfma_f32_16x16x32_bf16 v[38:41], v[170:173], v[194:197], v[38:41]
	v_mfma_f32_16x16x32_bf16 v[22:25], v[170:173], v[202:205], v[22:25]
	v_mfma_f32_16x16x32_bf16 v[14:17], v[178:181], v[202:205], v[14:17]
	v_mfma_f32_16x16x32_bf16 v[2:5], v[178:181], v[214:217], v[2:5]
	v_mfma_f32_16x16x32_bf16 v[6:9], v[170:173], v[214:217], v[6:9]
	v_mfma_f32_16x16x32_bf16 v[62:65], v[158:161], v[190:193], v[62:65]
	v_mfma_f32_16x16x32_bf16 v[58:61], v[166:169], v[190:193], v[58:61]
	v_mfma_f32_16x16x32_bf16 v[42:45], v[166:169], v[198:201], v[42:45]
	v_mfma_f32_16x16x32_bf16 v[50:53], v[158:161], v[198:201], v[50:53]
	v_mfma_f32_16x16x32_bf16 v[34:37], v[158:161], v[210:213], v[34:37]
	v_mfma_f32_16x16x32_bf16 v[26:29], v[166:169], v[210:213], v[26:29]
	v_mfma_f32_16x16x32_bf16 v[10:13], v[166:169], v[218:221], v[10:13]
	v_mfma_f32_16x16x32_bf16 v[18:21], v[158:161], v[218:221], v[18:21]
	v_mfma_f32_16x16x32_bf16 v[54:57], v[174:177], v[190:193], v[54:57]
	v_mfma_f32_16x16x32_bf16 v[46:49], v[182:185], v[190:193], v[46:49]
	v_mfma_f32_16x16x32_bf16 v[30:33], v[182:185], v[198:201], v[30:33]
	v_mfma_f32_16x16x32_bf16 v[38:41], v[174:177], v[198:201], v[38:41]
	v_mfma_f32_16x16x32_bf16 v[22:25], v[174:177], v[210:213], v[22:25]
	v_mfma_f32_16x16x32_bf16 v[14:17], v[182:185], v[210:213], v[14:17]
	v_mfma_f32_16x16x32_bf16 v[2:5], v[182:185], v[218:221], v[2:5]
	v_mfma_f32_16x16x32_bf16 v[6:9], v[174:177], v[218:221], v[6:9]
	s_barrier
	s_add_i32 s97, s97, 2
	s_add_u32 s90, s90, 0x100
	s_addc_u32 s91, s91, 0
	s_add_u32 s89, s89, 0x100
	s_addc_u32 s96, s96, 0
	s_cmp_gt_u32 s97, 13
	s_cbranch_scc0 .LBB0_75
	s_and_b64 vcc, exec, s[46:47]
	s_cbranch_vccz .LBB0_78
	s_barrier

.LBB0_188:
	s_add_i32 vcc_lo, s92, 2
	s_add_u32 s68, s40, 0x80
	s_addc_u32 s69, s41, 0
	s_add_i32 s70, 0, 0x10000
	s_cmp_eq_u32 s96, s92
	s_cselect_b32 s93, s89, s69
	s_cselect_b32 s92, s88, s68
	s_cselect_b32 s69, s91, s95
	s_cselect_b32 s68, s90, s94
	s_add_i32 s71, 0, 0x14000
	v_add_u32_e32 v126, s70, v162
	v_add_u32_e32 v172, s71, v162
	ds_read_b128 v[106:109], v126
	ds_read_b128 v[110:113], v126 offset:1024
	ds_read_b128 v[122:125], v126 offset:2048
	ds_read_b128 v[126:129], v126 offset:3072
	ds_read_b128 v[156:159], v172
	ds_read_b128 v[164:167], v172 offset:1024
	ds_read_b128 v[168:171], v172 offset:2048
	ds_read_b128 v[172:175], v172 offset:3072
	v_lshl_add_u64 v[210:211], s[40:41], 0, v[152:153]
	s_add_i32 m0, s19, 0xc000
	ds_read_b128 v[176:179], v163
	ds_read_b128 v[180:183], v163 offset:1024
	ds_read_b128 v[184:187], v163 offset:2048
	ds_read_b128 v[188:191], v163 offset:3072
	ds_read_b128 v[192:195], v163 offset:4096
	ds_read_b128 v[196:199], v163 offset:5120
	ds_read_b128 v[200:203], v163 offset:6144
	ds_read_b128 v[204:207], v163 offset:7168
	global_load_lds_dwordx4 v[210:211], off
	v_lshl_add_u64 v[210:211], s[40:41], 0, v[154:155]
	s_add_i32 m0, s19, 0xe000
	s_nop 0
	global_load_lds_dwordx4 v[210:211], off
	s_waitcnt vmcnt(8)
	s_waitcnt lgkmcnt(0)
	s_barrier
	s_waitcnt lgkmcnt(0)
	v_mfma_f32_16x16x32_bf16 v[142:145], v[106:109], v[176:179], v[142:145]
	v_mfma_f32_16x16x32_bf16 v[138:141], v[122:125], v[176:179], v[138:141]
	v_mfma_f32_16x16x32_bf16 v[114:117], v[122:125], v[184:187], v[114:117]
	v_mfma_f32_16x16x32_bf16 v[118:121], v[106:109], v[184:187], v[118:121]
	v_mfma_f32_16x16x32_bf16 v[94:97], v[106:109], v[192:195], v[94:97]
	v_mfma_f32_16x16x32_bf16 v[90:93], v[122:125], v[192:195], v[90:93]
	v_mfma_f32_16x16x32_bf16 v[74:77], v[122:125], v[200:203], v[74:77]
	v_mfma_f32_16x16x32_bf16 v[78:81], v[106:109], v[200:203], v[78:81]
	v_mfma_f32_16x16x32_bf16 v[134:137], v[156:159], v[176:179], v[134:137]
	v_mfma_f32_16x16x32_bf16 v[130:133], v[168:171], v[176:179], v[130:133]
	v_mfma_f32_16x16x32_bf16 v[98:101], v[168:171], v[184:187], v[98:101]
	v_mfma_f32_16x16x32_bf16 v[102:105], v[156:159], v[184:187], v[102:105]
	v_mfma_f32_16x16x32_bf16 v[86:89], v[156:159], v[192:195], v[86:89]
	v_mfma_f32_16x16x32_bf16 v[82:85], v[168:171], v[192:195], v[82:85]
	v_mfma_f32_16x16x32_bf16 v[66:69], v[168:171], v[200:203], v[66:69]
	v_mfma_f32_16x16x32_bf16 v[70:73], v[156:159], v[200:203], v[70:73]
	v_mfma_f32_16x16x32_bf16 v[142:145], v[110:113], v[180:183], v[142:145]
	v_mfma_f32_16x16x32_bf16 v[138:141], v[126:129], v[180:183], v[138:141]
	v_mfma_f32_16x16x32_bf16 v[114:117], v[126:129], v[188:191], v[114:117]
	v_mfma_f32_16x16x32_bf16 v[118:121], v[110:113], v[188:191], v[118:121]
	v_mfma_f32_16x16x32_bf16 v[94:97], v[110:113], v[196:199], v[94:97]
	v_mfma_f32_16x16x32_bf16 v[90:93], v[126:129], v[196:199], v[90:93]
	v_mfma_f32_16x16x32_bf16 v[74:77], v[126:129], v[204:207], v[74:77]
	v_mfma_f32_16x16x32_bf16 v[78:81], v[110:113], v[204:207], v[78:81]
	v_mfma_f32_16x16x32_bf16 v[134:137], v[164:167], v[180:183], v[134:137]
	v_mfma_f32_16x16x32_bf16 v[130:133], v[172:175], v[180:183], v[130:133]
	v_mfma_f32_16x16x32_bf16 v[98:101], v[172:175], v[188:191], v[98:101]
	v_mfma_f32_16x16x32_bf16 v[102:105], v[164:167], v[188:191], v[102:105]
	v_mfma_f32_16x16x32_bf16 v[86:89], v[164:167], v[196:199], v[86:89]
	v_mfma_f32_16x16x32_bf16 v[82:85], v[172:175], v[196:199], v[82:85]
	v_mfma_f32_16x16x32_bf16 v[66:69], v[172:175], v[204:207], v[66:69]
	v_mfma_f32_16x16x32_bf16 v[70:73], v[164:167], v[204:207], v[70:73]
	s_barrier
	s_add_i32 s70, s70, s18
	v_lshl_add_u64 v[210:211], s[68:69], 0, v[0:1]
	s_mov_b32 m0, s70
	ds_read_b128 v[176:179], v163 offset:16384
	ds_read_b128 v[180:183], v163 offset:17408
	ds_read_b128 v[184:187], v163 offset:18432
	ds_read_b128 v[188:191], v163 offset:19456
	ds_read_b128 v[192:195], v163 offset:20480
	ds_read_b128 v[196:199], v163 offset:21504
	ds_read_b128 v[200:203], v163 offset:22528
	ds_read_b128 v[204:207], v163 offset:23552
	global_load_lds_dwordx4 v[210:211], off
	s_add_i32 m0, s70, 0x2000
	v_lshl_add_u64 v[212:213], s[68:69], 0, v[150:151]
	s_add_u32 s68, s68, s26
	s_addc_u32 s69, s69, 0
	s_add_i32 s70, s71, s18
	global_load_lds_dwordx4 v[212:213], off
	v_lshl_add_u64 v[214:215], s[68:69], 0, v[0:1]
	s_mov_b32 m0, s70
	v_lshl_add_u64 v[216:217], s[68:69], 0, v[150:151]
	global_load_lds_dwordx4 v[214:215], off
	s_add_i32 m0, s70, 0x2000
	v_lshl_add_u64 v[218:219], s[92:93], 0, v[146:147]
	global_load_lds_dwordx4 v[216:217], off
	s_mov_b32 m0, s19
	v_lshl_add_u64 v[220:221], s[92:93], 0, v[148:149]
	global_load_lds_dwordx4 v[218:219], off
	s_mov_b32 m0, s20
	s_nop 0
	global_load_lds_dwordx4 v[220:221], off
	s_waitcnt vmcnt(8)
	s_waitcnt lgkmcnt(0)
	s_barrier
	s_waitcnt lgkmcnt(0)
	v_mfma_f32_16x16x32_bf16 v[62:65], v[106:109], v[176:179], v[62:65]
	v_mfma_f32_16x16x32_bf16 v[58:61], v[122:125], v[176:179], v[58:61]
	v_mfma_f32_16x16x32_bf16 v[42:45], v[122:125], v[184:187], v[42:45]
	v_mfma_f32_16x16x32_bf16 v[46:49], v[106:109], v[184:187], v[46:49]
	v_mfma_f32_16x16x32_bf16 v[30:33], v[106:109], v[192:195], v[30:33]
	v_mfma_f32_16x16x32_bf16 v[26:29], v[122:125], v[192:195], v[26:29]
	v_mfma_f32_16x16x32_bf16 v[10:13], v[122:125], v[200:203], v[10:13]
	v_mfma_f32_16x16x32_bf16 v[14:17], v[106:109], v[200:203], v[14:17]
	v_mfma_f32_16x16x32_bf16 v[54:57], v[156:159], v[176:179], v[54:57]
	v_mfma_f32_16x16x32_bf16 v[50:53], v[168:171], v[176:179], v[50:53]
	v_mfma_f32_16x16x32_bf16 v[34:37], v[168:171], v[184:187], v[34:37]
	v_mfma_f32_16x16x32_bf16 v[38:41], v[156:159], v[184:187], v[38:41]
	v_mfma_f32_16x16x32_bf16 v[22:25], v[156:159], v[192:195], v[22:25]
	v_mfma_f32_16x16x32_bf16 v[18:21], v[168:171], v[192:195], v[18:21]
	v_mfma_f32_16x16x32_bf16 v[2:5], v[168:171], v[200:203], v[2:5]
	v_mfma_f32_16x16x32_bf16 v[6:9], v[156:159], v[200:203], v[6:9]
	v_mfma_f32_16x16x32_bf16 v[62:65], v[110:113], v[180:183], v[62:65]
	v_mfma_f32_16x16x32_bf16 v[58:61], v[126:129], v[180:183], v[58:61]
	v_mfma_f32_16x16x32_bf16 v[42:45], v[126:129], v[188:191], v[42:45]
	v_mfma_f32_16x16x32_bf16 v[46:49], v[110:113], v[188:191], v[46:49]
	v_mfma_f32_16x16x32_bf16 v[30:33], v[110:113], v[196:199], v[30:33]
	v_mfma_f32_16x16x32_bf16 v[26:29], v[126:129], v[196:199], v[26:29]
	v_mfma_f32_16x16x32_bf16 v[10:13], v[126:129], v[204:207], v[10:13]
	v_mfma_f32_16x16x32_bf16 v[14:17], v[110:113], v[204:207], v[14:17]
	v_mfma_f32_16x16x32_bf16 v[54:57], v[164:167], v[180:183], v[54:57]
	v_mfma_f32_16x16x32_bf16 v[50:53], v[172:175], v[180:183], v[50:53]
	v_mfma_f32_16x16x32_bf16 v[34:37], v[172:175], v[188:191], v[34:37]
	v_mfma_f32_16x16x32_bf16 v[38:41], v[164:167], v[188:191], v[38:41]
	v_mfma_f32_16x16x32_bf16 v[22:25], v[164:167], v[196:199], v[22:25]
	v_mfma_f32_16x16x32_bf16 v[18:21], v[172:175], v[196:199], v[18:21]
	v_mfma_f32_16x16x32_bf16 v[2:5], v[172:175], v[204:207], v[2:5]
	v_mfma_f32_16x16x32_bf16 v[6:9], v[164:167], v[204:207], v[6:9]
	s_barrier
	s_add_i32 s70, 0, 0x18000
	s_add_i32 s71, 0, 0x1c000
	v_add_u32_e32 v126, s70, v162
	v_add_u32_e32 v172, s71, v162
	ds_read_b128 v[106:109], v126
	ds_read_b128 v[110:113], v126 offset:1024
	ds_read_b128 v[122:125], v126 offset:2048
	ds_read_b128 v[126:129], v126 offset:3072
	ds_read_b128 v[156:159], v172
	ds_read_b128 v[164:167], v172 offset:1024
	ds_read_b128 v[168:171], v172 offset:2048
	ds_read_b128 v[172:175], v172 offset:3072
	s_add_u32 s68, s92, s26
	s_addc_u32 s69, s93, 0
	s_mov_b32 m0, s21
	v_lshl_add_u64 v[222:223], s[68:69], 0, v[146:147]
	ds_read_b128 v[176:179], v163 offset:32768
	ds_read_b128 v[180:183], v163 offset:33792
	ds_read_b128 v[184:187], v163 offset:34816
	ds_read_b128 v[188:191], v163 offset:35840
	ds_read_b128 v[192:195], v163 offset:36864
	ds_read_b128 v[196:199], v163 offset:37888
	ds_read_b128 v[200:203], v163 offset:38912
	ds_read_b128 v[204:207], v163 offset:39936
	global_load_lds_dwordx4 v[222:223], off
	v_lshl_add_u64 v[222:223], s[68:69], 0, v[148:149]
	s_mov_b32 m0, s22
	s_nop 0
	global_load_lds_dwordx4 v[222:223], off
	s_waitcnt vmcnt(8)
	s_waitcnt lgkmcnt(0)
	s_barrier
	s_waitcnt lgkmcnt(0)
	v_mfma_f32_16x16x32_bf16 v[142:145], v[106:109], v[176:179], v[142:145]
	v_mfma_f32_16x16x32_bf16 v[138:141], v[122:125], v[176:179], v[138:141]
	v_mfma_f32_16x16x32_bf16 v[114:117], v[122:125], v[184:187], v[114:117]
	v_mfma_f32_16x16x32_bf16 v[118:121], v[106:109], v[184:187], v[118:121]
	v_mfma_f32_16x16x32_bf16 v[94:97], v[106:109], v[192:195], v[94:97]
	v_mfma_f32_16x16x32_bf16 v[90:93], v[122:125], v[192:195], v[90:93]
	v_mfma_f32_16x16x32_bf16 v[74:77], v[122:125], v[200:203], v[74:77]
	v_mfma_f32_16x16x32_bf16 v[78:81], v[106:109], v[200:203], v[78:81]
	v_mfma_f32_16x16x32_bf16 v[134:137], v[156:159], v[176:179], v[134:137]
	v_mfma_f32_16x16x32_bf16 v[130:133], v[168:171], v[176:179], v[130:133]
	v_mfma_f32_16x16x32_bf16 v[98:101], v[168:171], v[184:187], v[98:101]
	v_mfma_f32_16x16x32_bf16 v[102:105], v[156:159], v[184:187], v[102:105]
	v_mfma_f32_16x16x32_bf16 v[86:89], v[156:159], v[192:195], v[86:89]
	v_mfma_f32_16x16x32_bf16 v[82:85], v[168:171], v[192:195], v[82:85]
	v_mfma_f32_16x16x32_bf16 v[66:69], v[168:171], v[200:203], v[66:69]
	v_mfma_f32_16x16x32_bf16 v[70:73], v[156:159], v[200:203], v[70:73]
	v_mfma_f32_16x16x32_bf16 v[142:145], v[110:113], v[180:183], v[142:145]
	v_mfma_f32_16x16x32_bf16 v[138:141], v[126:129], v[180:183], v[138:141]
	v_mfma_f32_16x16x32_bf16 v[114:117], v[126:129], v[188:191], v[114:117]
	v_mfma_f32_16x16x32_bf16 v[118:121], v[110:113], v[188:191], v[118:121]
	v_mfma_f32_16x16x32_bf16 v[94:97], v[110:113], v[196:199], v[94:97]
	v_mfma_f32_16x16x32_bf16 v[90:93], v[126:129], v[196:199], v[90:93]
	v_mfma_f32_16x16x32_bf16 v[74:77], v[126:129], v[204:207], v[74:77]
	v_mfma_f32_16x16x32_bf16 v[78:81], v[110:113], v[204:207], v[78:81]
	v_mfma_f32_16x16x32_bf16 v[134:137], v[164:167], v[180:183], v[134:137]
	v_mfma_f32_16x16x32_bf16 v[130:133], v[172:175], v[180:183], v[130:133]
	v_mfma_f32_16x16x32_bf16 v[98:101], v[172:175], v[188:191], v[98:101]
	v_mfma_f32_16x16x32_bf16 v[102:105], v[164:167], v[188:191], v[102:105]
	v_mfma_f32_16x16x32_bf16 v[86:89], v[164:167], v[196:199], v[86:89]
	v_mfma_f32_16x16x32_bf16 v[82:85], v[172:175], v[196:199], v[82:85]
	v_mfma_f32_16x16x32_bf16 v[66:69], v[172:175], v[204:207], v[66:69]
	v_mfma_f32_16x16x32_bf16 v[70:73], v[164:167], v[204:207], v[70:73]
	s_barrier
	s_add_i32 s68, s70, s18
	v_lshl_add_u64 v[210:211], v[210:211], 0, s[34:35]
	s_mov_b32 m0, s68
	ds_read_b128 v[176:179], v163 offset:49152
	ds_read_b128 v[180:183], v163 offset:50176
	ds_read_b128 v[184:187], v163 offset:51200
	ds_read_b128 v[188:191], v163 offset:52224
	ds_read_b128 v[192:195], v163 offset:53248
	ds_read_b128 v[196:199], v163 offset:54272
	ds_read_b128 v[200:203], v163 offset:55296
	ds_read_b128 v[204:207], v163 offset:56320
	global_load_lds_dwordx4 v[210:211], off
	v_lshl_add_u64 v[210:211], v[212:213], 0, s[34:35]
	s_add_i32 m0, s68, 0x2000
	s_add_i32 s68, s71, s18
	global_load_lds_dwordx4 v[210:211], off
	v_lshl_add_u64 v[210:211], v[214:215], 0, s[34:35]
	s_mov_b32 m0, s68
	s_nop 0
	global_load_lds_dwordx4 v[210:211], off
	v_lshl_add_u64 v[210:211], v[216:217], 0, s[34:35]
	s_add_i32 m0, s68, 0x2000
	s_nop 0
	global_load_lds_dwordx4 v[210:211], off
	v_lshl_add_u64 v[210:211], v[218:219], 0, s[34:35]
	s_mov_b32 m0, s81
	s_nop 0
	global_load_lds_dwordx4 v[210:211], off
	v_lshl_add_u64 v[210:211], v[220:221], 0, s[34:35]
	s_mov_b32 m0, s83
	s_nop 0
	global_load_lds_dwordx4 v[210:211], off
	s_waitcnt vmcnt(8)
	s_waitcnt lgkmcnt(0)
	s_barrier
	s_waitcnt lgkmcnt(0)
	v_mfma_f32_16x16x32_bf16 v[62:65], v[106:109], v[176:179], v[62:65]
	v_mfma_f32_16x16x32_bf16 v[58:61], v[122:125], v[176:179], v[58:61]
	v_mfma_f32_16x16x32_bf16 v[42:45], v[122:125], v[184:187], v[42:45]
	v_mfma_f32_16x16x32_bf16 v[46:49], v[106:109], v[184:187], v[46:49]
	v_mfma_f32_16x16x32_bf16 v[30:33], v[106:109], v[192:195], v[30:33]
	v_mfma_f32_16x16x32_bf16 v[26:29], v[122:125], v[192:195], v[26:29]
	v_mfma_f32_16x16x32_bf16 v[10:13], v[122:125], v[200:203], v[10:13]
	v_mfma_f32_16x16x32_bf16 v[14:17], v[106:109], v[200:203], v[14:17]
	v_mfma_f32_16x16x32_bf16 v[54:57], v[156:159], v[176:179], v[54:57]
	v_mfma_f32_16x16x32_bf16 v[50:53], v[168:171], v[176:179], v[50:53]
	v_mfma_f32_16x16x32_bf16 v[34:37], v[168:171], v[184:187], v[34:37]
	v_mfma_f32_16x16x32_bf16 v[38:41], v[156:159], v[184:187], v[38:41]
	v_mfma_f32_16x16x32_bf16 v[22:25], v[156:159], v[192:195], v[22:25]
	v_mfma_f32_16x16x32_bf16 v[18:21], v[168:171], v[192:195], v[18:21]
	v_mfma_f32_16x16x32_bf16 v[2:5], v[168:171], v[200:203], v[2:5]
	v_mfma_f32_16x16x32_bf16 v[6:9], v[156:159], v[200:203], v[6:9]
	v_mfma_f32_16x16x32_bf16 v[62:65], v[110:113], v[180:183], v[62:65]
	v_mfma_f32_16x16x32_bf16 v[58:61], v[126:129], v[180:183], v[58:61]
	v_mfma_f32_16x16x32_bf16 v[42:45], v[126:129], v[188:191], v[42:45]
	v_mfma_f32_16x16x32_bf16 v[46:49], v[110:113], v[188:191], v[46:49]
	v_mfma_f32_16x16x32_bf16 v[30:33], v[110:113], v[196:199], v[30:33]
	v_mfma_f32_16x16x32_bf16 v[26:29], v[126:129], v[196:199], v[26:29]
	v_mfma_f32_16x16x32_bf16 v[10:13], v[126:129], v[204:207], v[10:13]
	v_mfma_f32_16x16x32_bf16 v[14:17], v[110:113], v[204:207], v[14:17]
	v_mfma_f32_16x16x32_bf16 v[54:57], v[164:167], v[180:183], v[54:57]
	v_mfma_f32_16x16x32_bf16 v[50:53], v[172:175], v[180:183], v[50:53]
	v_mfma_f32_16x16x32_bf16 v[34:37], v[172:175], v[188:191], v[34:37]
	v_mfma_f32_16x16x32_bf16 v[38:41], v[164:167], v[188:191], v[38:41]
	v_mfma_f32_16x16x32_bf16 v[22:25], v[164:167], v[196:199], v[22:25]
	v_mfma_f32_16x16x32_bf16 v[18:21], v[172:175], v[196:199], v[18:21]
	v_mfma_f32_16x16x32_bf16 v[2:5], v[172:175], v[204:207], v[2:5]
	v_mfma_f32_16x16x32_bf16 v[6:9], v[164:167], v[204:207], v[6:9]
	s_barrier
	s_add_u32 s40, s40, 0x100
	s_addc_u32 s41, s41, 0
	s_add_u32 s94, s94, 0x100
	s_addc_u32 s95, s95, 0
	s_cmp_ge_u32 vcc_lo, s29
	s_mov_b32 s92, vcc_lo
	s_cbranch_scc0 .LBB0_188
	s_and_b64 vcc, exec, s[78:79]
	s_cbranch_vccz .LBB0_191
	s_barrier

.LBB0_243:
	s_add_u32 s70, s42, 0xfffc0080
	s_addc_u32 s71, s43, -1
	s_add_i32 s72, 0, 0x10000
	s_cmp_eq_u32 s95, 12
	s_cselect_b32 vcc_hi, s2, s71
	s_cselect_b32 vcc_lo, s6, s70
	v_add_u32_e32 v0, s72, v181
	s_cselect_b32 s93, s41, s89
	s_cselect_b32 s92, s48, s77
	s_add_i32 s73, 0, 0x14000
	ds_read_b128 v[14:17], v0
	ds_read_b128 v[22:25], v0 offset:1024
	ds_read_b128 v[26:29], v0 offset:2048
	ds_read_b128 v[74:77], v0 offset:3072
	v_add_u32_e32 v0, s73, v181
	ds_read_b128 v[78:81], v0
	ds_read_b128 v[82:85], v0 offset:1024
	ds_read_b128 v[154:157], v0 offset:2048
	ds_read_b128 v[158:161], v0 offset:3072
	v_lshl_add_u64 v[174:175], s[42:43], 0, v[170:171]
	s_add_i32 m0, s81, 0xc000
	ds_read_b128 v[182:185], v189
	ds_read_b128 v[190:193], v189 offset:1024
	ds_read_b128 v[194:197], v189 offset:2048
	ds_read_b128 v[198:201], v189 offset:3072
	ds_read_b128 v[202:205], v189 offset:4096
	ds_read_b128 v[210:213], v189 offset:5120
	ds_read_b128 v[214:217], v189 offset:6144
	ds_read_b128 v[218:221], v189 offset:7168
	global_load_lds_dwordx4 v[174:175], off
	v_lshl_add_u64 v[174:175], s[42:43], 0, v[172:173]
	s_add_i32 m0, s81, 0xe000
	s_nop 0
	global_load_lds_dwordx4 v[174:175], off
	s_waitcnt vmcnt(8)
	s_waitcnt lgkmcnt(0)
	s_barrier
	s_waitcnt lgkmcnt(0)
	v_mfma_f32_16x16x32_bf16 v[150:153], v[14:17], v[182:185], v[150:153]
	v_mfma_f32_16x16x32_bf16 v[58:61], v[26:29], v[182:185], v[58:61]
	v_mfma_f32_16x16x32_bf16 v[122:125], v[26:29], v[194:197], v[122:125]
	v_mfma_f32_16x16x32_bf16 v[126:129], v[14:17], v[194:197], v[126:129]
	v_mfma_f32_16x16x32_bf16 v[118:121], v[14:17], v[202:205], v[118:121]
	v_mfma_f32_16x16x32_bf16 v[114:117], v[26:29], v[202:205], v[114:117]
	v_mfma_f32_16x16x32_bf16 v[130:133], v[26:29], v[214:217], v[130:133]
	v_mfma_f32_16x16x32_bf16 v[134:137], v[14:17], v[214:217], v[134:137]
	v_mfma_f32_16x16x32_bf16 v[142:145], v[78:81], v[182:185], v[142:145]
	v_mfma_f32_16x16x32_bf16 v[138:141], v[154:157], v[182:185], v[138:141]
	v_mfma_f32_16x16x32_bf16 v[106:109], v[154:157], v[194:197], v[106:109]
	v_mfma_f32_16x16x32_bf16 v[110:113], v[78:81], v[194:197], v[110:113]
	v_mfma_f32_16x16x32_bf16 v[102:105], v[78:81], v[202:205], v[102:105]
	v_mfma_f32_16x16x32_bf16 v[98:101], v[154:157], v[202:205], v[98:101]
	v_mfma_f32_16x16x32_bf16 v[90:93], v[154:157], v[214:217], v[90:93]
	v_mfma_f32_16x16x32_bf16 v[94:97], v[78:81], v[214:217], v[94:97]
	v_mfma_f32_16x16x32_bf16 v[150:153], v[22:25], v[190:193], v[150:153]
	v_mfma_f32_16x16x32_bf16 v[58:61], v[74:77], v[190:193], v[58:61]
	v_mfma_f32_16x16x32_bf16 v[122:125], v[74:77], v[198:201], v[122:125]
	v_mfma_f32_16x16x32_bf16 v[126:129], v[22:25], v[198:201], v[126:129]
	v_mfma_f32_16x16x32_bf16 v[118:121], v[22:25], v[210:213], v[118:121]
	v_mfma_f32_16x16x32_bf16 v[114:117], v[74:77], v[210:213], v[114:117]
	v_mfma_f32_16x16x32_bf16 v[130:133], v[74:77], v[218:221], v[130:133]
	v_mfma_f32_16x16x32_bf16 v[134:137], v[22:25], v[218:221], v[134:137]
	v_mfma_f32_16x16x32_bf16 v[142:145], v[82:85], v[190:193], v[142:145]
	v_mfma_f32_16x16x32_bf16 v[138:141], v[158:161], v[190:193], v[138:141]
	v_mfma_f32_16x16x32_bf16 v[106:109], v[158:161], v[198:201], v[106:109]
	v_mfma_f32_16x16x32_bf16 v[110:113], v[82:85], v[198:201], v[110:113]
	v_mfma_f32_16x16x32_bf16 v[102:105], v[82:85], v[210:213], v[102:105]
	v_mfma_f32_16x16x32_bf16 v[98:101], v[158:161], v[210:213], v[98:101]
	v_mfma_f32_16x16x32_bf16 v[90:93], v[158:161], v[218:221], v[90:93]
	v_mfma_f32_16x16x32_bf16 v[94:97], v[82:85], v[218:221], v[94:97]
	s_barrier
	s_add_i32 s70, s72, s29
	v_lshl_add_u64 v[174:175], s[92:93], 0, v[164:165]
	s_mov_b32 m0, s70
	ds_read_b128 v[182:185], v189 offset:16384
	ds_read_b128 v[190:193], v189 offset:17408
	ds_read_b128 v[194:197], v189 offset:18432
	ds_read_b128 v[198:201], v189 offset:19456
	ds_read_b128 v[202:205], v189 offset:20480
	ds_read_b128 v[210:213], v189 offset:21504
	ds_read_b128 v[214:217], v189 offset:22528
	ds_read_b128 v[218:221], v189 offset:23552
	global_load_lds_dwordx4 v[174:175], off
	s_add_i32 m0, s70, 0x2000
	s_add_u32 s70, s92, 0x40000
	v_lshl_add_u64 v[186:187], s[92:93], 0, v[168:169]
	s_addc_u32 s71, s93, 0
	s_add_i32 s72, s73, s29
	global_load_lds_dwordx4 v[186:187], off
	v_lshl_add_u64 v[206:207], s[70:71], 0, v[164:165]
	s_mov_b32 m0, s72
	v_lshl_add_u64 v[226:227], vcc, 0, v[166:167]
	global_load_lds_dwordx4 v[206:207], off
	v_lshl_add_u64 v[206:207], s[70:71], 0, v[168:169]
	s_add_i32 m0, s72, 0x2000
	s_nop 0
	global_load_lds_dwordx4 v[206:207], off
	v_lshl_add_u64 v[206:207], vcc, 0, v[162:163]
	s_mov_b32 m0, s81
	s_nop 0
	global_load_lds_dwordx4 v[206:207], off
	s_mov_b32 m0, s83
	s_nop 0
	global_load_lds_dwordx4 v[226:227], off
	s_waitcnt vmcnt(8)
	s_waitcnt lgkmcnt(0)
	s_barrier
	s_waitcnt lgkmcnt(0)
	v_mfma_f32_16x16x32_bf16 v[70:73], v[14:17], v[182:185], v[70:73]
	v_mfma_f32_16x16x32_bf16 v[66:69], v[26:29], v[182:185], v[66:69]
	v_mfma_f32_16x16x32_bf16 v[54:57], v[26:29], v[194:197], v[54:57]
	v_mfma_f32_16x16x32_bf16 v[62:65], v[14:17], v[194:197], v[62:65]
	v_mfma_f32_16x16x32_bf16 v[42:45], v[14:17], v[202:205], v[42:45]
	v_mfma_f32_16x16x32_bf16 v[38:41], v[26:29], v[202:205], v[38:41]
	v_mfma_f32_16x16x32_bf16 v[14:17], v[14:17], v[214:217], v[86:89]
	v_mfma_f32_16x16x32_bf16 v[46:49], v[154:157], v[182:185], v[46:49]
	v_mfma_f32_16x16x32_bf16 v[34:37], v[78:81], v[194:197], v[34:37]
	v_mfma_f32_16x16x32_bf16 v[30:33], v[154:157], v[194:197], v[30:33]
	v_mfma_f32_16x16x32_bf16 v[10:13], v[154:157], v[202:205], v[10:13]
	v_mfma_f32_16x16x32_bf16 v[18:21], v[78:81], v[202:205], v[18:21]
	v_mfma_f32_16x16x32_bf16 v[6:9], v[78:81], v[214:217], v[6:9]
	v_mfma_f32_16x16x32_bf16 v[2:5], v[154:157], v[214:217], v[2:5]
	v_mfma_f32_16x16x32_bf16 v[70:73], v[22:25], v[190:193], v[70:73]
	v_mfma_f32_16x16x32_bf16 v[66:69], v[74:77], v[190:193], v[66:69]
	v_mfma_f32_16x16x32_bf16 v[54:57], v[74:77], v[198:201], v[54:57]
	v_mfma_f32_16x16x32_bf16 v[62:65], v[22:25], v[198:201], v[62:65]
	v_mfma_f32_16x16x32_bf16 v[42:45], v[22:25], v[210:213], v[42:45]
	v_mfma_f32_16x16x32_bf16 v[38:41], v[74:77], v[210:213], v[38:41]
	v_mfma_f32_16x16x32_bf16 v[14:17], v[22:25], v[218:221], v[14:17]
	v_mfma_f32_16x16x32_bf16 v[22:25], v[26:29], v[214:217], v[146:149]
	v_mfma_f32_16x16x32_bf16 v[26:29], v[78:81], v[182:185], v[50:53]
	v_mfma_f32_16x16x32_bf16 v[46:49], v[158:161], v[190:193], v[46:49]
	v_mfma_f32_16x16x32_bf16 v[34:37], v[82:85], v[198:201], v[34:37]
	v_mfma_f32_16x16x32_bf16 v[30:33], v[158:161], v[198:201], v[30:33]
	v_mfma_f32_16x16x32_bf16 v[10:13], v[158:161], v[210:213], v[10:13]
	v_mfma_f32_16x16x32_bf16 v[18:21], v[82:85], v[210:213], v[18:21]
	v_mfma_f32_16x16x32_bf16 v[6:9], v[82:85], v[218:221], v[6:9]
	v_mfma_f32_16x16x32_bf16 v[2:5], v[158:161], v[218:221], v[2:5]
	v_mfma_f32_16x16x32_bf16 v[22:25], v[74:77], v[218:221], v[22:25]
	v_mfma_f32_16x16x32_bf16 v[26:29], v[82:85], v[190:193], v[26:29]
	s_barrier
	s_add_i32 s72, 0, 0x18000
	v_add_u32_e32 v0, s72, v181
	s_add_i32 s73, 0, 0x1c000
	ds_read_b128 v[50:53], v0
	ds_read_b128 v[74:77], v0 offset:1024
	ds_read_b128 v[78:81], v0 offset:2048
	ds_read_b128 v[82:85], v0 offset:3072
	v_add_u32_e32 v0, s73, v181
	ds_read_b128 v[154:157], v0
	ds_read_b128 v[158:161], v0 offset:1024
	ds_read_b128 v[182:185], v0 offset:2048
	ds_read_b128 v[190:193], v0 offset:3072
	s_add_u32 s70, vcc_lo, 0x40000
	s_addc_u32 s71, vcc_hi, 0
	s_mov_b32 m0, s16
	v_lshl_add_u64 v[222:223], s[70:71], 0, v[162:163]
	ds_read_b128 v[86:89], v189 offset:32768
	ds_read_b128 v[146:149], v189 offset:33792
	ds_read_b128 v[194:197], v189 offset:34816
	ds_read_b128 v[198:201], v189 offset:35840
	ds_read_b128 v[202:205], v189 offset:36864
	ds_read_b128 v[210:213], v189 offset:37888
	ds_read_b128 v[214:217], v189 offset:38912
	ds_read_b128 v[218:221], v189 offset:39936
	global_load_lds_dwordx4 v[222:223], off
	v_lshl_add_u64 v[222:223], s[70:71], 0, v[166:167]
	s_mov_b32 m0, s17
	s_nop 0
	global_load_lds_dwordx4 v[222:223], off
	s_waitcnt vmcnt(8)
	s_waitcnt lgkmcnt(0)
	s_barrier
	s_waitcnt lgkmcnt(0)
	v_mfma_f32_16x16x32_bf16 v[150:153], v[50:53], v[86:89], v[150:153]
	v_mfma_f32_16x16x32_bf16 v[58:61], v[78:81], v[86:89], v[58:61]
	v_mfma_f32_16x16x32_bf16 v[142:145], v[154:157], v[86:89], v[142:145]
	v_mfma_f32_16x16x32_bf16 v[86:89], v[182:185], v[86:89], v[138:141]
	v_mfma_f32_16x16x32_bf16 v[138:141], v[190:193], v[146:149], v[86:89]
	v_mfma_f32_16x16x32_bf16 v[86:89], v[154:157], v[194:197], v[110:113]
	v_mfma_f32_16x16x32_bf16 v[110:113], v[158:161], v[198:201], v[86:89]
	v_mfma_f32_16x16x32_bf16 v[86:89], v[182:185], v[194:197], v[106:109]
	v_mfma_f32_16x16x32_bf16 v[106:109], v[190:193], v[198:201], v[86:89]
	v_mfma_f32_16x16x32_bf16 v[86:89], v[154:157], v[202:205], v[102:105]
	v_mfma_f32_16x16x32_bf16 v[102:105], v[158:161], v[210:213], v[86:89]
	v_mfma_f32_16x16x32_bf16 v[86:89], v[182:185], v[202:205], v[98:101]
	v_mfma_f32_16x16x32_bf16 v[98:101], v[190:193], v[210:213], v[86:89]
	v_mfma_f32_16x16x32_bf16 v[86:89], v[154:157], v[214:217], v[94:97]
	v_mfma_f32_16x16x32_bf16 v[126:129], v[50:53], v[194:197], v[126:129]
	v_mfma_f32_16x16x32_bf16 v[122:125], v[78:81], v[194:197], v[122:125]
	v_mfma_f32_16x16x32_bf16 v[114:117], v[78:81], v[202:205], v[114:117]
	v_mfma_f32_16x16x32_bf16 v[118:121], v[50:53], v[202:205], v[118:121]
	v_mfma_f32_16x16x32_bf16 v[134:137], v[50:53], v[214:217], v[134:137]
	v_mfma_f32_16x16x32_bf16 v[130:133], v[78:81], v[214:217], v[130:133]
	v_mfma_f32_16x16x32_bf16 v[94:97], v[158:161], v[218:221], v[86:89]
	v_mfma_f32_16x16x32_bf16 v[86:89], v[182:185], v[214:217], v[90:93]
	v_mfma_f32_16x16x32_bf16 v[150:153], v[74:77], v[146:149], v[150:153]
	v_mfma_f32_16x16x32_bf16 v[58:61], v[82:85], v[146:149], v[58:61]
	v_mfma_f32_16x16x32_bf16 v[122:125], v[82:85], v[198:201], v[122:125]
	v_mfma_f32_16x16x32_bf16 v[126:129], v[74:77], v[198:201], v[126:129]
	v_mfma_f32_16x16x32_bf16 v[118:121], v[74:77], v[210:213], v[118:121]
	v_mfma_f32_16x16x32_bf16 v[114:117], v[82:85], v[210:213], v[114:117]
	v_mfma_f32_16x16x32_bf16 v[130:133], v[82:85], v[218:221], v[130:133]
	v_mfma_f32_16x16x32_bf16 v[134:137], v[74:77], v[218:221], v[134:137]
	v_mfma_f32_16x16x32_bf16 v[142:145], v[158:161], v[146:149], v[142:145]
	v_mfma_f32_16x16x32_bf16 v[90:93], v[190:193], v[218:221], v[86:89]
	s_barrier
	s_add_i32 s70, s72, s29
	v_lshl_add_u64 v[86:87], v[174:175], 0, s[34:35]
	s_mov_b32 m0, s70
	ds_read_b128 v[194:197], v189 offset:49152
	ds_read_b128 v[198:201], v189 offset:50176
	ds_read_b128 v[202:205], v189 offset:51200
	ds_read_b128 v[210:213], v189 offset:52224
	ds_read_b128 v[214:217], v189 offset:53248
	ds_read_b128 v[218:221], v189 offset:54272
	ds_read_b128 v[222:225], v189 offset:55296
	ds_read_b128 v[242:245], v189 offset:56320
	global_load_lds_dwordx4 v[86:87], off
	s_add_i32 m0, s70, 0x2000
	s_add_u32 s70, s92, 0x40080
	v_lshl_add_u64 v[86:87], v[186:187], 0, s[34:35]
	s_addc_u32 s71, s93, 0
	s_add_i32 s72, s73, s29
	global_load_lds_dwordx4 v[86:87], off
	v_lshl_add_u64 v[86:87], s[70:71], 0, v[164:165]
	s_mov_b32 m0, s72
	s_nop 0
	global_load_lds_dwordx4 v[86:87], off
	v_lshl_add_u64 v[86:87], s[70:71], 0, v[168:169]
	s_add_i32 m0, s72, 0x2000
	s_nop 0
	global_load_lds_dwordx4 v[86:87], off
	v_lshl_add_u64 v[86:87], v[206:207], 0, s[34:35]
	s_mov_b32 m0, s19
	s_nop 0
	global_load_lds_dwordx4 v[86:87], off
	v_lshl_add_u64 v[86:87], v[226:227], 0, s[34:35]
	s_mov_b32 m0, s20
	s_nop 0
	global_load_lds_dwordx4 v[86:87], off
	s_waitcnt vmcnt(8)
	s_waitcnt lgkmcnt(0)
	s_barrier
	s_waitcnt lgkmcnt(0)
	v_mfma_f32_16x16x32_bf16 v[14:17], v[50:53], v[222:225], v[14:17]
	v_mfma_f32_16x16x32_bf16 v[86:89], v[74:77], v[242:245], v[14:17]
	v_mfma_f32_16x16x32_bf16 v[14:17], v[78:81], v[222:225], v[22:25]
	v_mfma_f32_16x16x32_bf16 v[146:149], v[82:85], v[242:245], v[14:17]
	v_mfma_f32_16x16x32_bf16 v[14:17], v[154:157], v[194:197], v[26:29]
	v_mfma_f32_16x16x32_bf16 v[70:73], v[50:53], v[194:197], v[70:73]
	v_mfma_f32_16x16x32_bf16 v[62:65], v[50:53], v[202:205], v[62:65]
	v_mfma_f32_16x16x32_bf16 v[42:45], v[50:53], v[214:217], v[42:45]
	v_mfma_f32_16x16x32_bf16 v[50:53], v[158:161], v[198:201], v[14:17]
	v_mfma_f32_16x16x32_bf16 v[14:17], v[182:185], v[194:197], v[46:49]
	v_mfma_f32_16x16x32_bf16 v[46:49], v[190:193], v[198:201], v[14:17]
	v_mfma_f32_16x16x32_bf16 v[14:17], v[154:157], v[202:205], v[34:37]
	v_mfma_f32_16x16x32_bf16 v[34:37], v[158:161], v[210:213], v[14:17]
	v_mfma_f32_16x16x32_bf16 v[14:17], v[182:185], v[202:205], v[30:33]
	v_mfma_f32_16x16x32_bf16 v[66:69], v[78:81], v[194:197], v[66:69]
	v_mfma_f32_16x16x32_bf16 v[54:57], v[78:81], v[202:205], v[54:57]
	v_mfma_f32_16x16x32_bf16 v[38:41], v[78:81], v[214:217], v[38:41]
	v_mfma_f32_16x16x32_bf16 v[30:33], v[190:193], v[210:213], v[14:17]
	v_mfma_f32_16x16x32_bf16 v[14:17], v[154:157], v[214:217], v[18:21]
	v_mfma_f32_16x16x32_bf16 v[10:13], v[182:185], v[214:217], v[10:13]
	v_mfma_f32_16x16x32_bf16 v[6:9], v[154:157], v[222:225], v[6:9]
	v_mfma_f32_16x16x32_bf16 v[2:5], v[182:185], v[222:225], v[2:5]
	v_mfma_f32_16x16x32_bf16 v[70:73], v[74:77], v[198:201], v[70:73]
	v_mfma_f32_16x16x32_bf16 v[66:69], v[82:85], v[198:201], v[66:69]
	v_mfma_f32_16x16x32_bf16 v[54:57], v[82:85], v[210:213], v[54:57]
	v_mfma_f32_16x16x32_bf16 v[62:65], v[74:77], v[210:213], v[62:65]
	v_mfma_f32_16x16x32_bf16 v[42:45], v[74:77], v[218:221], v[42:45]
	v_mfma_f32_16x16x32_bf16 v[38:41], v[82:85], v[218:221], v[38:41]
	v_mfma_f32_16x16x32_bf16 v[18:21], v[158:161], v[218:221], v[14:17]
	v_mfma_f32_16x16x32_bf16 v[10:13], v[190:193], v[218:221], v[10:13]
	v_mfma_f32_16x16x32_bf16 v[6:9], v[158:161], v[242:245], v[6:9]
	v_mfma_f32_16x16x32_bf16 v[2:5], v[190:193], v[242:245], v[2:5]
	s_barrier
	s_add_i32 s95, s95, 2
	s_add_u32 s42, s42, 0x100
	s_addc_u32 s43, s43, 0
	s_add_u32 s77, s77, 0x100
	s_addc_u32 s89, s89, 0
	s_cmp_gt_u32 s95, 13
	s_cbranch_scc0 .LBB0_243
	s_and_b64 vcc, exec, s[74:75]
	s_cbranch_vccz .LBB0_246
	s_barrier
